# nt policy also on the P0 mod-GEMV weight loads and read-once transposed weight loads
# speedup vs baseline: 1.0459x; 1.0047x over previous
.LBB0_24:
	s_load_dwordx2 s[8:9], s[8:9], 0x0
	s_lshl_b32 s10, s2, 7
	s_lshl_b32 s11, s33, 4
	s_and_b32 s10, s10, 0x600
	s_and_b32 s11, s11, 0x700
	s_add_i32 s10, s10, s11
	s_lshl_b32 s11, s33, 3
	s_lshl_b32 s21, s2, 16
	s_and_b32 s10, s10, 0x600
	s_and_b32 s11, s11, 0x80
	s_and_b32 s21, s21, 0xc0000
	s_waitcnt lgkmcnt(0)
	s_add_u32 s21, s8, s21
	s_addc_u32 s27, s9, 0
	s_lshl_b32 s8, s2, 6
	s_and_b32 s28, s8, 0xc0
	s_add_u32 s26, s21, s24
	v_or_b32_e32 v11, s28, v1
	s_addc_u32 s27, s27, s25
	v_lshl_add_u64 v[12:13], s[26:27], 0, v[6:7]
	v_lshlrev_b32_e32 v14, 10, v11
	v_mov_b32_e32 v15, v7
	v_lshl_add_u64 v[12:13], v[12:13], 0, v[14:15]
	v_add_co_u32_e32 v14, vcc, s45, v12
	s_movk_i32 s21, 0x3000
	s_nop 0
	v_addc_co_u32_e32 v15, vcc, 0, v13, vcc
	v_add_co_u32_e32 v16, vcc, s46, v12
	s_mov_b64 s[8:9], s[0:1]
	s_nop 0
	v_addc_co_u32_e32 v17, vcc, 0, v13, vcc
	v_add_co_u32_e32 v18, vcc, s21, v12
	s_movk_i32 s21, 0x5000
	s_nop 0
	v_addc_co_u32_e32 v19, vcc, 0, v13, vcc
	v_add_co_u32_e32 v20, vcc, s47, v12
	s_nop 1
	v_addc_co_u32_e32 v21, vcc, 0, v13, vcc
	global_load_dword v11, v[16:17], off offset:-4096 nt
	global_load_dword v32, v[16:17], off nt
	global_load_dword v33, v[16:17], off offset:2048 nt
	global_load_dword v34, v[20:21], off offset:-4096 nt
	global_load_dword v35, v[20:21], off nt
	v_add_co_u32_e32 v16, vcc, s21, v12
	s_movk_i32 s21, 0x7000
	s_nop 0
	v_addc_co_u32_e32 v17, vcc, 0, v13, vcc
	v_add_co_u32_e32 v22, vcc, s17, v12
	s_nop 1
	v_addc_co_u32_e32 v23, vcc, 0, v13, vcc
	v_add_co_u32_e32 v24, vcc, s21, v12
	s_mov_b32 s21, 0x9000
	s_nop 0
	v_addc_co_u32_e32 v25, vcc, 0, v13, vcc
	v_add_co_u32_e32 v26, vcc, s48, v12
	s_nop 1
	v_addc_co_u32_e32 v27, vcc, 0, v13, vcc
	v_add_co_u32_e32 v28, vcc, s21, v12
	s_mov_b32 s21, 0xd000
	s_nop 0
	v_addc_co_u32_e32 v29, vcc, 0, v13, vcc
	v_add_co_u32_e32 v30, vcc, s49, v12
	s_nop 1
	v_addc_co_u32_e32 v31, vcc, 0, v13, vcc
	global_load_dword v59, v[20:21], off offset:2048 nt
	global_load_dword v60, v[22:23], off offset:-4096 nt
	global_load_dword v61, v[22:23], off nt
	global_load_dword v62, v[22:23], off offset:2048 nt
	global_load_dword v63, v[26:27], off offset:-4096 nt
	global_load_dword v64, v[26:27], off nt
	s_nop 0
	global_load_dword v26, v[26:27], off offset:2048 nt
	s_nop 0
	global_load_dword v27, v[30:31], off offset:-4096 nt
	v_add_co_u32_e32 v20, vcc, s50, v12
	s_nop 1
	v_addc_co_u32_e32 v21, vcc, 0, v13, vcc
	v_add_co_u32_e32 v22, vcc, s51, v12
	global_load_dword v65, v[12:13], off nt
	global_load_dword v66, v[12:13], off offset:2048 nt
	global_load_dword v67, v[14:15], off offset:2048 nt
	s_nop 0
	global_load_dword v18, v[18:19], off offset:2048 nt
	s_nop 0
	global_load_dword v19, v[16:17], off offset:2048 nt
	s_nop 0
	global_load_dword v24, v[24:25], off offset:2048 nt
	s_nop 0
	global_load_dword v25, v[28:29], off offset:2048 nt
	s_nop 0
	global_load_dword v20, v[20:21], off offset:2048 nt
	v_addc_co_u32_e32 v23, vcc, 0, v13, vcc
	v_add_co_u32_e32 v14, vcc, s21, v12
	s_mov_b32 s21, 0xf000
	s_nop 0
	v_addc_co_u32_e32 v15, vcc, 0, v13, vcc
	v_add_co_u32_e32 v16, vcc, s52, v12
	s_nop 1
	v_addc_co_u32_e32 v17, vcc, 0, v13, vcc
	v_add_co_u32_e32 v12, vcc, s21, v12
	global_load_dword v21, v[30:31], off nt
	global_load_dword v28, v[30:31], off offset:2048 nt
	global_load_dword v29, v[22:23], off offset:-4096 nt
	s_nop 0
	global_load_dword v30, v[22:23], off nt
	s_nop 0
	global_load_dword v22, v[22:23], off offset:2048 nt
	s_nop 0
	global_load_dword v23, v[16:17], off offset:-4096 nt
	global_load_dword v31, v[16:17], off nt
	s_nop 0
	global_load_dword v16, v[16:17], off offset:2048 nt
	v_addc_co_u32_e32 v13, vcc, 0, v13, vcc
	global_load_dword v14, v[14:15], off offset:2048 nt
	s_nop 0
	global_load_dword v15, v[12:13], off nt
	s_nop 0
	global_load_dword v12, v[12:13], off offset:2048 nt
	s_load_dwordx2 s[26:27], s[8:9], 0xa0
	s_lshl_b32 s9, s28, 1
	s_mov_b32 s8, 0
	v_mov_b32_e32 v17, v41
	s_waitcnt vmcnt(17)
	ds_write2_b32 v3, v65, v66 offset1:66
	s_waitcnt vmcnt(16)
	ds_write2_b32 v3, v11, v67 offset0:132 offset1:198
	ds_write2_b32 v50, v32, v33 offset0:8 offset1:74
	s_waitcnt vmcnt(15)
	ds_write2_b32 v50, v34, v18 offset0:140 offset1:206
	ds_write2_b32 v51, v35, v59 offset0:16 offset1:82
	s_waitcnt vmcnt(14)
	ds_write2_b32 v51, v60, v19 offset0:148 offset1:214
	ds_write2_b32 v52, v61, v62 offset0:24 offset1:90
	s_waitcnt vmcnt(13)
	ds_write2_b32 v52, v63, v24 offset0:156 offset1:222
	ds_write2_b32 v53, v64, v26 offset0:32 offset1:98
	s_waitcnt vmcnt(12)
	ds_write2_b32 v53, v27, v25 offset0:164 offset1:230
	s_waitcnt vmcnt(9)
	ds_write2_b32 v54, v21, v28 offset0:40 offset1:106
	s_waitcnt vmcnt(8)
	ds_write2_b32 v54, v29, v20 offset0:172 offset1:238
	s_waitcnt vmcnt(6)
	ds_write2_b32 v55, v30, v22 offset0:48 offset1:114
	s_waitcnt vmcnt(2)
	ds_write2_b32 v55, v23, v14 offset0:180 offset1:246
	ds_write2_b32 v56, v31, v16 offset0:56 offset1:122
	s_waitcnt vmcnt(0)
	ds_write2_b32 v56, v15, v12 offset0:188 offset1:254
	s_waitcnt lgkmcnt(0)
	s_add_u32 s26, s26, s9
	s_waitcnt lgkmcnt(0)
	s_addc_u32 s27, s27, 0
	v_mov_b32_e32 v11, v7
	v_lshl_add_u64 v[12:13], s[26:27], 0, v[10:11]
	s_mov_b64 s[26:27], 0x2900000
	s_or_b32 s9, s10, s11
	v_lshl_add_u64 v[12:13], v[12:13], 0, s[26:27]
	s_or_b32 s21, s9, 16
	v_mov_b32_e32 v11, v47
	v_mov_b32_e32 v14, v39
	v_mov_b32_e32 v15, v45
	v_mov_b32_e32 v16, v43
	v_mov_b32_e32 v18, v40

.LBB0_27:
	s_and_b64 vcc, exec, s[8:9]
	s_cbranch_vccz .LBB0_31
	s_lshl_b32 s8, s41, 4
	s_and_b32 s26, s8, 0xffffff00
	s_mov_b64 s[8:9], s[0:1]
	s_add_i32 s10, s2, 0xfffffb70
	s_load_dwordx2 s[28:29], s[8:9], 0x70
	s_lshl_b32 s8, s2, 6
	s_and_b32 s21, s8, 0x3c0
	s_lshr_b32 s8, s10, 1
	s_and_b32 s8, s8, 0x7fffff8
	s_add_i32 s8, s8, s3
	s_lshl_b32 s30, s8, 5
	s_ashr_i32 s31, s30, 31
	s_lshl_b64 s[30:31], s[30:31], 2
	s_waitcnt lgkmcnt(0)
	s_add_u32 s28, s28, s30
	v_or_b32_e32 v11, s21, v1
	s_addc_u32 s29, s29, s31
	v_lshl_add_u64 v[12:13], s[28:29], 0, v[6:7]
	v_lshlrev_b32_e32 v14, 12, v11
	v_mov_b32_e32 v15, v7
	v_lshl_add_u64 v[12:13], v[12:13], 0, v[14:15]
	v_add_co_u32_e32 v14, vcc, s46, v12
	s_mov_b64 s[8:9], s[0:1]
	s_nop 0
	v_addc_co_u32_e32 v15, vcc, 0, v13, vcc
	v_add_co_u32_e32 v16, vcc, s47, v12
	s_mov_b32 s10, 0x10000
	s_nop 0
	v_addc_co_u32_e32 v17, vcc, 0, v13, vcc
	v_add_co_u32_e32 v18, vcc, s17, v12
	s_nop 1
	v_addc_co_u32_e32 v19, vcc, 0, v13, vcc
	v_add_co_u32_e32 v20, vcc, s48, v12
	s_nop 1
	v_addc_co_u32_e32 v21, vcc, 0, v13, vcc
	v_add_co_u32_e32 v22, vcc, s49, v12
	s_nop 1
	v_addc_co_u32_e32 v23, vcc, 0, v13, vcc
	v_add_co_u32_e32 v24, vcc, s51, v12
	s_nop 1
	v_addc_co_u32_e32 v25, vcc, 0, v13, vcc
	v_add_co_u32_e32 v26, vcc, s52, v12
	s_nop 1
	v_addc_co_u32_e32 v27, vcc, 0, v13, vcc
	global_load_dword v11, v[12:13], off nt
	global_load_dword v30, v[14:15], off nt
	global_load_dword v31, v[16:17], off nt
	global_load_dword v32, v[18:19], off nt
	global_load_dword v33, v[20:21], off nt
	global_load_dword v34, v[22:23], off nt
	global_load_dword v35, v[24:25], off nt
	global_load_dword v59, v[26:27], off nt
	v_add_co_u32_e32 v14, vcc, s10, v12
	s_mov_b32 s10, 0x12000
	s_nop 0
	v_addc_co_u32_e32 v15, vcc, 0, v13, vcc
	v_add_co_u32_e32 v16, vcc, s10, v12
	s_mov_b32 s10, 0x14000
	s_nop 0
	v_addc_co_u32_e32 v17, vcc, 0, v13, vcc
	v_add_co_u32_e32 v18, vcc, s10, v12
	s_mov_b32 s10, 0x1a000
	s_nop 0
	v_addc_co_u32_e32 v19, vcc, 0, v13, vcc
	v_add_co_u32_e32 v20, vcc, s56, v12
	s_nop 1
	v_addc_co_u32_e32 v21, vcc, 0, v13, vcc
	v_add_co_u32_e32 v22, vcc, s11, v12
	s_nop 1
	v_addc_co_u32_e32 v23, vcc, 0, v13, vcc
	v_add_co_u32_e32 v24, vcc, s10, v12
	s_mov_b32 s10, 0x1e000
	s_nop 0
	v_addc_co_u32_e32 v25, vcc, 0, v13, vcc
	v_add_co_u32_e32 v26, vcc, s16, v12
	s_nop 1
	v_addc_co_u32_e32 v27, vcc, 0, v13, vcc
	v_add_co_u32_e32 v28, vcc, s10, v12
	s_mov_b32 s10, 0x20000
	s_nop 0
	v_addc_co_u32_e32 v29, vcc, 0, v13, vcc
	global_load_dword v60, v[14:15], off nt
	global_load_dword v61, v[16:17], off nt
	global_load_dword v62, v[18:19], off nt
	global_load_dword v63, v[20:21], off nt
	global_load_dword v64, v[22:23], off nt
	global_load_dword v65, v[24:25], off nt
	global_load_dword v66, v[26:27], off nt
	global_load_dword v67, v[28:29], off nt
	v_add_co_u32_e32 v14, vcc, s10, v12
	s_mov_b32 s10, 0x22000
	s_nop 0
	v_addc_co_u32_e32 v15, vcc, 0, v13, vcc
	v_add_co_u32_e32 v16, vcc, s10, v12
	s_mov_b32 s10, 0x24000
	s_nop 0
	v_addc_co_u32_e32 v17, vcc, 0, v13, vcc
	v_add_co_u32_e32 v18, vcc, s10, v12
	s_mov_b32 s10, 0x26000
	s_nop 0
	v_addc_co_u32_e32 v19, vcc, 0, v13, vcc
	v_add_co_u32_e32 v20, vcc, s10, v12
	s_mov_b32 s10, 0x28000
	s_nop 0
	v_addc_co_u32_e32 v21, vcc, 0, v13, vcc
	v_add_co_u32_e32 v22, vcc, s10, v12
	s_mov_b32 s10, 0x2e000
	s_nop 0
	v_addc_co_u32_e32 v23, vcc, 0, v13, vcc
	v_add_co_u32_e32 v24, vcc, s64, v12
	s_nop 1
	v_addc_co_u32_e32 v25, vcc, 0, v13, vcc
	v_add_co_u32_e32 v26, vcc, s65, v12
	s_nop 1
	v_addc_co_u32_e32 v27, vcc, 0, v13, vcc
	v_add_co_u32_e32 v28, vcc, s10, v12
	s_mov_b32 s10, 0x30000
	s_nop 0
	v_addc_co_u32_e32 v29, vcc, 0, v13, vcc
	global_load_dword v68, v[14:15], off nt
	global_load_dword v69, v[16:17], off nt
	global_load_dword v70, v[18:19], off nt
	global_load_dword v71, v[20:21], off nt
	global_load_dword v72, v[22:23], off nt
	global_load_dword v73, v[24:25], off nt
	global_load_dword v74, v[26:27], off nt
	s_nop 0
	global_load_dword v28, v[28:29], off nt
	v_add_co_u32_e32 v14, vcc, s10, v12
	s_mov_b32 s10, 0x34000
	s_nop 0
	v_addc_co_u32_e32 v15, vcc, 0, v13, vcc
	v_add_co_u32_e32 v16, vcc, s67, v12
	s_nop 1
	v_addc_co_u32_e32 v17, vcc, 0, v13, vcc
	v_add_co_u32_e32 v18, vcc, s10, v12
	s_lshl_b32 s10, s21, 1
	s_nop 0
	v_addc_co_u32_e32 v19, vcc, 0, v13, vcc
	v_add_co_u32_e32 v20, vcc, s70, v12
	s_nop 1
	v_addc_co_u32_e32 v21, vcc, 0, v13, vcc
	v_add_co_u32_e32 v22, vcc, s71, v12
	s_nop 1
	v_addc_co_u32_e32 v23, vcc, 0, v13, vcc
	v_add_co_u32_e32 v24, vcc, s72, v12
	s_nop 1
	v_addc_co_u32_e32 v25, vcc, 0, v13, vcc
	v_add_co_u32_e32 v26, vcc, s73, v12
	s_nop 1
	v_addc_co_u32_e32 v27, vcc, 0, v13, vcc
	v_add_co_u32_e32 v12, vcc, s74, v12
	s_nop 1
	v_addc_co_u32_e32 v13, vcc, 0, v13, vcc
	global_load_dword v15, v[14:15], off nt
	s_nop 0
	global_load_dword v16, v[16:17], off nt
	s_nop 0
	global_load_dword v17, v[18:19], off nt
	s_nop 0
	global_load_dword v18, v[20:21], off nt
	global_load_dword v19, v[22:23], off nt
	s_nop 0
	global_load_dword v20, v[24:25], off nt
	global_load_dword v21, v[26:27], off nt
	s_nop 0
	global_load_dword v12, v[12:13], off nt
	s_load_dwordx2 s[8:9], s[8:9], 0xa0
	s_waitcnt vmcnt(30)
	ds_write2_b32 v3, v11, v30 offset1:66
	s_waitcnt vmcnt(28)
	ds_write2_b32 v3, v31, v32 offset0:132 offset1:198
	s_waitcnt vmcnt(26)
	ds_write2_b32 v50, v33, v34 offset0:8 offset1:74
	s_waitcnt vmcnt(24)
	ds_write2_b32 v50, v35, v59 offset0:140 offset1:206
	s_waitcnt vmcnt(22)
	ds_write2_b32 v51, v60, v61 offset0:16 offset1:82
	s_waitcnt vmcnt(20)
	ds_write2_b32 v51, v62, v63 offset0:148 offset1:214
	s_waitcnt vmcnt(18)
	ds_write2_b32 v52, v64, v65 offset0:24 offset1:90
	s_waitcnt vmcnt(16)
	ds_write2_b32 v52, v66, v67 offset0:156 offset1:222
	s_waitcnt vmcnt(14)
	ds_write2_b32 v53, v68, v69 offset0:32 offset1:98
	s_waitcnt vmcnt(12)
	ds_write2_b32 v53, v70, v71 offset0:164 offset1:230
	s_waitcnt vmcnt(10)
	ds_write2_b32 v54, v72, v73 offset0:40 offset1:106
	s_waitcnt vmcnt(8)
	ds_write2_b32 v54, v74, v28 offset0:172 offset1:238
	s_waitcnt vmcnt(6)
	ds_write2_b32 v55, v15, v16 offset0:48 offset1:114
	s_waitcnt vmcnt(4)
	ds_write2_b32 v55, v17, v18 offset0:180 offset1:246
	s_waitcnt vmcnt(2)
	ds_write2_b32 v56, v19, v20 offset0:56 offset1:122
	s_waitcnt vmcnt(0)
	ds_write2_b32 v56, v21, v12 offset0:188 offset1:254
	s_waitcnt lgkmcnt(0)
	s_waitcnt lgkmcnt(0)
	s_add_u32 s8, s8, s10
	s_addc_u32 s9, s9, 0
	v_mov_b32_e32 v11, v7
	v_lshl_add_u64 v[12:13], s[8:9], 0, v[10:11]
	s_mov_b64 s[8:9], 0x2700000
	v_add_u32_e32 v14, s26, v39
	v_lshl_add_u64 v[12:13], v[12:13], 0, s[8:9]
	s_mov_b32 s8, 16
	v_mov_b32_e32 v11, v47

.LBB0_32:
	s_andn2_b64 vcc, exec, s[8:9]
	s_cbranch_vccnz .LBB0_36
	s_mov_b64 s[8:9], s[0:1]
	s_load_dwordx2 s[28:29], s[8:9], 0x88
	s_add_i32 s8, s2, 32
	s_and_b32 s9, s8, 0xff
	s_mulk_i32 s9, 0xbb
	s_bfe_u32 s9, s9, 0x3000d
	s_lshl_b32 s21, s9, 8
	s_mul_i32 s10, s9, 44
	s_add_i32 s30, s21, s20
	s_sub_i32 s8, s8, s10
	s_ashr_i32 s31, s30, 31
	s_and_b32 s26, s8, 0xff
	s_lshl_b64 s[30:31], s[30:31], 2
	s_waitcnt lgkmcnt(0)
	s_add_u32 s28, s28, s30
	s_addc_u32 s29, s29, s31
	v_lshlrev_b32_e32 v11, 12, v1
	v_lshl_add_u64 v[12:13], s[28:29], 0, v[6:7]
	v_lshl_or_b32 v14, s26, 18, v11
	v_mov_b32_e32 v15, v7
	v_lshl_add_u64 v[12:13], v[12:13], 0, v[14:15]
	v_add_co_u32_e32 v14, vcc, s46, v12
	s_mov_b64 s[8:9], s[0:1]
	s_nop 0
	v_addc_co_u32_e32 v15, vcc, 0, v13, vcc
	v_add_co_u32_e32 v16, vcc, s47, v12
	s_mov_b32 s10, 0x10000
	s_nop 0
	v_addc_co_u32_e32 v17, vcc, 0, v13, vcc
	v_add_co_u32_e32 v18, vcc, s17, v12
	s_nop 1
	v_addc_co_u32_e32 v19, vcc, 0, v13, vcc
	v_add_co_u32_e32 v20, vcc, s48, v12
	s_nop 1
	v_addc_co_u32_e32 v21, vcc, 0, v13, vcc
	v_add_co_u32_e32 v22, vcc, s49, v12
	s_nop 1
	v_addc_co_u32_e32 v23, vcc, 0, v13, vcc
	v_add_co_u32_e32 v24, vcc, s51, v12
	s_nop 1
	v_addc_co_u32_e32 v25, vcc, 0, v13, vcc
	v_add_co_u32_e32 v26, vcc, s52, v12
	s_nop 1
	v_addc_co_u32_e32 v27, vcc, 0, v13, vcc
	global_load_dword v11, v[12:13], off nt
	global_load_dword v30, v[14:15], off nt
	global_load_dword v31, v[16:17], off nt
	global_load_dword v32, v[18:19], off nt
	global_load_dword v33, v[20:21], off nt
	global_load_dword v34, v[22:23], off nt
	global_load_dword v35, v[24:25], off nt
	global_load_dword v59, v[26:27], off nt
	v_add_co_u32_e32 v14, vcc, s10, v12
	s_mov_b32 s10, 0x12000
	s_nop 0
	v_addc_co_u32_e32 v15, vcc, 0, v13, vcc
	v_add_co_u32_e32 v16, vcc, s10, v12
	s_mov_b32 s10, 0x14000
	s_nop 0
	v_addc_co_u32_e32 v17, vcc, 0, v13, vcc
	v_add_co_u32_e32 v18, vcc, s10, v12
	s_mov_b32 s10, 0x1a000
	s_nop 0
	v_addc_co_u32_e32 v19, vcc, 0, v13, vcc
	v_add_co_u32_e32 v20, vcc, s56, v12
	s_nop 1
	v_addc_co_u32_e32 v21, vcc, 0, v13, vcc
	v_add_co_u32_e32 v22, vcc, s11, v12
	s_nop 1
	v_addc_co_u32_e32 v23, vcc, 0, v13, vcc
	v_add_co_u32_e32 v24, vcc, s10, v12
	s_mov_b32 s10, 0x1e000
	s_nop 0
	v_addc_co_u32_e32 v25, vcc, 0, v13, vcc
	v_add_co_u32_e32 v26, vcc, s16, v12
	s_nop 1
	v_addc_co_u32_e32 v27, vcc, 0, v13, vcc
	v_add_co_u32_e32 v28, vcc, s10, v12
	s_mov_b32 s10, 0x20000
	s_nop 0
	v_addc_co_u32_e32 v29, vcc, 0, v13, vcc
	global_load_dword v60, v[14:15], off nt
	global_load_dword v61, v[16:17], off nt
	global_load_dword v62, v[18:19], off nt
	global_load_dword v63, v[20:21], off nt
	global_load_dword v64, v[22:23], off nt
	global_load_dword v65, v[24:25], off nt
	global_load_dword v66, v[26:27], off nt
	global_load_dword v67, v[28:29], off nt
	v_add_co_u32_e32 v14, vcc, s10, v12
	s_mov_b32 s10, 0x22000
	s_nop 0
	v_addc_co_u32_e32 v15, vcc, 0, v13, vcc
	v_add_co_u32_e32 v16, vcc, s10, v12
	s_mov_b32 s10, 0x24000
	s_nop 0
	v_addc_co_u32_e32 v17, vcc, 0, v13, vcc
	v_add_co_u32_e32 v18, vcc, s10, v12
	s_mov_b32 s10, 0x26000
	s_nop 0
	v_addc_co_u32_e32 v19, vcc, 0, v13, vcc
	v_add_co_u32_e32 v20, vcc, s10, v12
	s_mov_b32 s10, 0x28000
	s_nop 0
	v_addc_co_u32_e32 v21, vcc, 0, v13, vcc
	v_add_co_u32_e32 v22, vcc, s10, v12
	s_mov_b32 s10, 0x2e000
	s_nop 0
	v_addc_co_u32_e32 v23, vcc, 0, v13, vcc
	v_add_co_u32_e32 v24, vcc, s64, v12
	s_nop 1
	v_addc_co_u32_e32 v25, vcc, 0, v13, vcc
	v_add_co_u32_e32 v26, vcc, s65, v12
	s_nop 1
	v_addc_co_u32_e32 v27, vcc, 0, v13, vcc
	v_add_co_u32_e32 v28, vcc, s10, v12
	s_mov_b32 s10, 0x30000
	s_nop 0
	v_addc_co_u32_e32 v29, vcc, 0, v13, vcc
	global_load_dword v68, v[14:15], off nt
	global_load_dword v69, v[16:17], off nt
	global_load_dword v70, v[18:19], off nt
	global_load_dword v71, v[20:21], off nt
	global_load_dword v72, v[22:23], off nt
	global_load_dword v73, v[24:25], off nt
	global_load_dword v74, v[26:27], off nt
	s_nop 0
	global_load_dword v28, v[28:29], off nt
	v_add_co_u32_e32 v14, vcc, s10, v12
	s_mov_b32 s10, 0x34000
	s_nop 0
	v_addc_co_u32_e32 v15, vcc, 0, v13, vcc
	v_add_co_u32_e32 v16, vcc, s67, v12
	s_nop 1
	v_addc_co_u32_e32 v17, vcc, 0, v13, vcc
	v_add_co_u32_e32 v18, vcc, s10, v12
	s_lshl_b32 s10, s26, 7
	s_nop 0
	v_addc_co_u32_e32 v19, vcc, 0, v13, vcc
	v_add_co_u32_e32 v20, vcc, s70, v12
	s_nop 1
	v_addc_co_u32_e32 v21, vcc, 0, v13, vcc
	v_add_co_u32_e32 v22, vcc, s71, v12
	s_nop 1
	v_addc_co_u32_e32 v23, vcc, 0, v13, vcc
	v_add_co_u32_e32 v24, vcc, s72, v12
	s_nop 1
	v_addc_co_u32_e32 v25, vcc, 0, v13, vcc
	v_add_co_u32_e32 v26, vcc, s73, v12
	s_nop 1
	v_addc_co_u32_e32 v27, vcc, 0, v13, vcc
	v_add_co_u32_e32 v12, vcc, s74, v12
	s_nop 1
	v_addc_co_u32_e32 v13, vcc, 0, v13, vcc
	global_load_dword v14, v[14:15], off nt
	s_nop 0
	global_load_dword v15, v[16:17], off nt
	s_nop 0
	global_load_dword v16, v[18:19], off nt
	global_load_dword v17, v[20:21], off nt
	s_nop 0
	global_load_dword v18, v[22:23], off nt
	global_load_dword v19, v[24:25], off nt
	global_load_dword v20, v[26:27], off nt
	s_nop 0
	global_load_dword v12, v[12:13], off nt
	s_load_dwordx2 s[8:9], s[8:9], 0xa0
	s_waitcnt vmcnt(30)
	ds_write2_b32 v3, v11, v30 offset1:66
	s_waitcnt vmcnt(28)
	ds_write2_b32 v3, v31, v32 offset0:132 offset1:198
	s_waitcnt vmcnt(26)
	ds_write2_b32 v50, v33, v34 offset0:8 offset1:74
	s_waitcnt vmcnt(24)
	ds_write2_b32 v50, v35, v59 offset0:140 offset1:206
	s_waitcnt vmcnt(22)
	ds_write2_b32 v51, v60, v61 offset0:16 offset1:82
	s_waitcnt vmcnt(20)
	ds_write2_b32 v51, v62, v63 offset0:148 offset1:214
	s_waitcnt vmcnt(18)
	ds_write2_b32 v52, v64, v65 offset0:24 offset1:90
	s_waitcnt vmcnt(16)
	ds_write2_b32 v52, v66, v67 offset0:156 offset1:222
	s_waitcnt vmcnt(14)
	ds_write2_b32 v53, v68, v69 offset0:32 offset1:98
	s_waitcnt vmcnt(12)
	ds_write2_b32 v53, v70, v71 offset0:164 offset1:230
	s_waitcnt vmcnt(10)
	ds_write2_b32 v54, v72, v73 offset0:40 offset1:106
	s_waitcnt vmcnt(8)
	ds_write2_b32 v54, v74, v28 offset0:172 offset1:238
	s_waitcnt vmcnt(6)
	ds_write2_b32 v55, v14, v15 offset0:48 offset1:114
	s_waitcnt vmcnt(4)
	ds_write2_b32 v55, v16, v17 offset0:180 offset1:246
	s_waitcnt vmcnt(2)
	ds_write2_b32 v56, v18, v19 offset0:56 offset1:122
	s_waitcnt vmcnt(0)
	ds_write2_b32 v56, v20, v12 offset0:188 offset1:254
	s_waitcnt lgkmcnt(0)
	s_add_u32 s8, s8, s10
	s_waitcnt lgkmcnt(0)
	s_addc_u32 s9, s9, 0
	v_mov_b32_e32 v11, v7
	v_lshl_add_u64 v[12:13], s[8:9], 0, v[10:11]
	s_mov_b64 s[8:9], 0x2100000
	v_lshl_add_u64 v[12:13], v[12:13], 0, s[8:9]
	v_add_u32_e32 v11, s21, v39
	s_mov_b32 s8, 16
	v_mov_b32_e32 v14, v47

.LBB0_42:
	s_andn2_b64 vcc, exec, s[8:9]
	s_cbranch_vccnz .LBB0_108
	s_add_i32 s21, s2, 0xffffff40
	s_lshr_b32 s8, s21, 6
	s_cmp_gt_i32 s8, 5
	s_mov_b64 s[26:27], -1
	s_cbranch_scc1 .LBB0_104
	s_add_i32 s8, s8, -3
	s_cmp_lt_u32 s8, 2
	s_cselect_b64 s[26:27], -1, 0
	s_cmp_gt_u32 s8, 1
	s_cbranch_scc0 .LBB0_104
	s_lshr_b32 s8, s42, 4
	s_lshl_b32 s29, s8, 8
	s_lshl_b32 s9, s8, 9
	s_lshl_b32 s8, s8, 10
	s_add_i32 s61, s40, s9
	s_add_i32 s62, s43, s8
	s_mov_b64 s[8:9], s[0:1]
	s_load_dwordx2 s[30:31], s[8:9], 0x28
	s_lshl_b32 s8, s2, 6
	s_and_b32 s28, s8, 0x3c0
	s_lshr_b32 s8, s21, 1
	s_and_b32 s8, s8, 0x7fffff8
	s_add_i32 s8, s8, s3
	s_lshl_b32 s34, s8, 5
	s_ashr_i32 s35, s34, 31
	s_lshl_b64 s[34:35], s[34:35], 2
	v_or_b32_e32 v11, s28, v1
	s_waitcnt lgkmcnt(0)
	s_add_u32 s30, s30, s34
	s_addc_u32 s31, s31, s35
	v_mul_u32_u24_e32 v11, 0x1c00, v11
	v_lshl_add_u64 v[12:13], s[30:31], 0, v[6:7]
	v_lshlrev_b32_e32 v14, 2, v11
	v_mov_b32_e32 v15, v7
	v_lshl_add_u64 v[12:13], v[12:13], 0, v[14:15]
	v_add_co_u32_e32 v14, vcc, s52, v12
	s_mov_b64 s[8:9], s[0:1]
	s_nop 0
	v_addc_co_u32_e32 v15, vcc, 0, v13, vcc
	v_add_co_u32_e32 v16, vcc, s16, v12
	s_lshl_b32 s10, s28, 1
	s_nop 0
	v_addc_co_u32_e32 v17, vcc, 0, v13, vcc
	v_add_co_u32_e32 v18, vcc, s64, v12
	s_mov_b32 s63, 0
	s_nop 0
	v_addc_co_u32_e32 v19, vcc, 0, v13, vcc
	v_add_co_u32_e32 v20, vcc, s71, v12
	s_mov_b32 s66, 0
	s_nop 0
	v_addc_co_u32_e32 v21, vcc, 0, v13, vcc
	v_add_co_u32_e32 v22, vcc, s78, v12
	s_nop 1
	v_addc_co_u32_e32 v23, vcc, 0, v13, vcc
	v_add_co_u32_e32 v24, vcc, s79, v12
	s_nop 1
	v_addc_co_u32_e32 v25, vcc, 0, v13, vcc
	v_add_co_u32_e32 v26, vcc, s80, v12
	s_nop 1
	v_addc_co_u32_e32 v27, vcc, 0, v13, vcc
	global_load_dword v11, v[12:13], off nt
	global_load_dword v30, v[14:15], off nt
	global_load_dword v31, v[16:17], off nt
	global_load_dword v32, v[18:19], off nt
	global_load_dword v33, v[20:21], off nt
	global_load_dword v34, v[22:23], off nt
	global_load_dword v35, v[24:25], off nt
	global_load_dword v59, v[26:27], off nt
	v_add_co_u32_e32 v14, vcc, s81, v12
	s_nop 1
	v_addc_co_u32_e32 v15, vcc, 0, v13, vcc
	v_add_co_u32_e32 v16, vcc, s82, v12
	s_nop 1
	v_addc_co_u32_e32 v17, vcc, 0, v13, vcc
	v_add_co_u32_e32 v18, vcc, s83, v12
	s_nop 1
	v_addc_co_u32_e32 v19, vcc, 0, v13, vcc
	v_add_co_u32_e32 v20, vcc, s76, v12
	s_nop 1
	v_addc_co_u32_e32 v21, vcc, 0, v13, vcc
	v_add_co_u32_e32 v22, vcc, s84, v12
	s_nop 1
	v_addc_co_u32_e32 v23, vcc, 0, v13, vcc
	v_add_co_u32_e32 v24, vcc, s85, v12
	s_nop 1
	v_addc_co_u32_e32 v25, vcc, 0, v13, vcc
	v_add_co_u32_e32 v26, vcc, s86, v12
	s_nop 1
	v_addc_co_u32_e32 v27, vcc, 0, v13, vcc
	v_add_co_u32_e32 v28, vcc, s87, v12
	s_nop 1
	v_addc_co_u32_e32 v29, vcc, 0, v13, vcc
	global_load_dword v60, v[14:15], off nt
	global_load_dword v61, v[16:17], off nt
	global_load_dword v62, v[18:19], off nt
	global_load_dword v63, v[20:21], off nt
	global_load_dword v64, v[22:23], off nt
	global_load_dword v65, v[24:25], off nt
	global_load_dword v66, v[26:27], off nt
	global_load_dword v67, v[28:29], off nt
	v_add_co_u32_e32 v14, vcc, s88, v12
	s_nop 1
	v_addc_co_u32_e32 v15, vcc, 0, v13, vcc
	v_add_co_u32_e32 v16, vcc, s89, v12
	s_nop 1
	v_addc_co_u32_e32 v17, vcc, 0, v13, vcc
	v_add_co_u32_e32 v18, vcc, s90, v12
	s_nop 1
	v_addc_co_u32_e32 v19, vcc, 0, v13, vcc
	v_add_co_u32_e32 v20, vcc, s91, v12
	s_nop 1
	v_addc_co_u32_e32 v21, vcc, 0, v13, vcc
	v_add_co_u32_e32 v22, vcc, s92, v12
	s_nop 1
	v_addc_co_u32_e32 v23, vcc, 0, v13, vcc
	v_add_co_u32_e32 v24, vcc, s93, v12
	s_nop 1
	v_addc_co_u32_e32 v25, vcc, 0, v13, vcc
	v_add_co_u32_e32 v26, vcc, s77, v12
	s_nop 1
	v_addc_co_u32_e32 v27, vcc, 0, v13, vcc
	v_add_co_u32_e32 v28, vcc, s94, v12
	s_nop 1
	v_addc_co_u32_e32 v29, vcc, 0, v13, vcc
	global_load_dword v68, v[14:15], off nt
	global_load_dword v69, v[16:17], off nt
	global_load_dword v70, v[18:19], off nt
	global_load_dword v71, v[20:21], off nt
	global_load_dword v72, v[22:23], off nt
	global_load_dword v73, v[24:25], off nt
	global_load_dword v74, v[26:27], off nt
	s_nop 0
	global_load_dword v28, v[28:29], off nt
	v_add_co_u32_e32 v14, vcc, s95, v12
	s_nop 1
	v_addc_co_u32_e32 v15, vcc, 0, v13, vcc
	v_add_co_u32_e32 v16, vcc, s96, v12
	s_nop 1
	v_addc_co_u32_e32 v17, vcc, 0, v13, vcc
	v_add_co_u32_e32 v18, vcc, s97, v12
	s_nop 1
	v_addc_co_u32_e32 v19, vcc, 0, v13, vcc
	v_add_co_u32_e32 v20, vcc, s44, v12
	s_nop 1
	v_addc_co_u32_e32 v21, vcc, 0, v13, vcc
	v_add_co_u32_e32 v22, vcc, s53, v12
	s_nop 1
	v_addc_co_u32_e32 v23, vcc, 0, v13, vcc
	v_add_co_u32_e32 v24, vcc, s54, v12
	s_nop 1
	v_addc_co_u32_e32 v25, vcc, 0, v13, vcc
	v_add_co_u32_e32 v26, vcc, s55, v12
	s_nop 1
	v_addc_co_u32_e32 v27, vcc, 0, v13, vcc
	v_add_co_u32_e32 v12, vcc, s57, v12
	s_nop 1
	v_addc_co_u32_e32 v13, vcc, 0, v13, vcc
	global_load_dword v14, v[14:15], off nt
	s_nop 0
	global_load_dword v15, v[16:17], off nt
	s_nop 0
	global_load_dword v16, v[18:19], off nt
	global_load_dword v17, v[20:21], off nt
	s_nop 0
	global_load_dword v20, v[22:23], off nt
	global_load_dword v21, v[24:25], off nt
	s_nop 0
	global_load_dword v22, v[26:27], off nt
	s_nop 0
	global_load_dword v12, v[12:13], off nt
	s_load_dwordx2 s[8:9], s[8:9], 0xa0
	s_waitcnt vmcnt(30)
	ds_write2_b32 v3, v11, v30 offset1:66
	s_waitcnt vmcnt(28)
	ds_write2_b32 v3, v31, v32 offset0:132 offset1:198
	s_waitcnt vmcnt(26)
	ds_write2_b32 v50, v33, v34 offset0:8 offset1:74
	s_waitcnt vmcnt(24)
	ds_write2_b32 v50, v35, v59 offset0:140 offset1:206
	s_waitcnt vmcnt(22)
	ds_write2_b32 v51, v60, v61 offset0:16 offset1:82
	s_waitcnt vmcnt(20)
	ds_write2_b32 v51, v62, v63 offset0:148 offset1:214
	s_waitcnt vmcnt(18)
	ds_write2_b32 v52, v64, v65 offset0:24 offset1:90
	s_waitcnt vmcnt(16)
	ds_write2_b32 v52, v66, v67 offset0:156 offset1:222
	s_waitcnt vmcnt(14)
	ds_write2_b32 v53, v68, v69 offset0:32 offset1:98
	s_waitcnt vmcnt(12)
	ds_write2_b32 v53, v70, v71 offset0:164 offset1:230
	s_waitcnt vmcnt(10)
	ds_write2_b32 v54, v72, v73 offset0:40 offset1:106
	s_waitcnt vmcnt(8)
	ds_write2_b32 v54, v74, v28 offset0:172 offset1:238
	s_waitcnt vmcnt(6)
	ds_write2_b32 v55, v14, v15 offset0:48 offset1:114
	s_waitcnt vmcnt(4)
	ds_write2_b32 v55, v16, v17 offset0:180 offset1:246
	s_waitcnt vmcnt(2)
	ds_write2_b32 v56, v20, v21 offset0:56 offset1:122
	s_waitcnt vmcnt(0)
	ds_write2_b32 v56, v22, v12 offset0:188 offset1:254
	s_waitcnt lgkmcnt(0)
	s_add_u32 s8, s8, s10
	s_waitcnt lgkmcnt(0)
	s_addc_u32 s9, s9, 0
	v_mov_b32_e32 v11, v7
	v_lshl_add_u64 v[12:13], s[8:9], 0, v[10:11]
	s_mov_b64 s[8:9], 0x800000
	v_add_lshl_u32 v18, v42, s29, 2
	v_add_u32_e32 v19, s29, v38
	v_lshl_add_u64 v[12:13], v[12:13], 0, s[8:9]
	v_mov_b32_e32 v11, v5
	s_branch .LBB0_47

.LBB0_111:
	v_add_u32_e32 v59, s9, v48
	v_add_u32_e32 v108, 2, v59
	v_add_u32_e32 v110, 4, v59
	v_add_u32_e32 v112, 6, v59
	v_add_u32_e32 v114, 8, v59
	v_add_u32_e32 v116, 10, v59
	v_add_u32_e32 v118, 12, v59
	v_add_u32_e32 v120, 14, v59
	v_add_u32_e32 v122, 16, v59
	v_add_u32_e32 v124, 18, v59
	v_add_u32_e32 v126, 20, v59
	v_add_u32_e32 v128, 22, v59
	v_add_u32_e32 v130, 24, v59
	v_add_u32_e32 v132, 26, v59
	v_add_u32_e32 v134, 28, v59
	v_add_u32_e32 v136, 30, v59
	v_add_u32_e32 v59, 32, v59
	v_add_u32_e32 v102, 0x1000, v11
	v_add_u32_e32 v104, 0x2000, v11
	v_add_u32_e32 v106, 0x3000, v11
	v_mad_i64_i32 v[108:109], s[26:27], v108, s17, v[14:15]
	v_mad_i64_i32 v[110:111], s[26:27], v110, s17, v[14:15]
	v_mad_i64_i32 v[112:113], s[26:27], v112, s17, v[14:15]
	v_mad_i64_i32 v[114:115], s[26:27], v114, s17, v[14:15]
	v_mad_i64_i32 v[116:117], s[26:27], v116, s17, v[14:15]
	v_mad_i64_i32 v[118:119], s[26:27], v118, s17, v[14:15]
	v_mad_i64_i32 v[120:121], s[26:27], v120, s17, v[14:15]
	v_mad_i64_i32 v[122:123], s[26:27], v122, s17, v[14:15]
	v_mad_i64_i32 v[124:125], s[26:27], v124, s17, v[14:15]
	v_mad_i64_i32 v[126:127], s[26:27], v126, s17, v[14:15]
	v_mad_i64_i32 v[128:129], s[26:27], v128, s17, v[14:15]
	v_mad_i64_i32 v[130:131], s[26:27], v130, s17, v[14:15]
	v_mad_i64_i32 v[132:133], s[26:27], v132, s17, v[14:15]
	v_mad_i64_i32 v[134:135], s[26:27], v134, s17, v[14:15]
	v_mad_i64_i32 v[136:137], s[26:27], v136, s17, v[14:15]
	v_mad_i64_i32 v[138:139], s[26:27], v59, s17, v[14:15]
	ds_read2_b32 v[26:27], v11 offset1:2
	ds_read2_b32 v[24:25], v11 offset0:4 offset1:6
	ds_read2_b32 v[20:21], v11 offset0:8 offset1:10
	ds_read2_b32 v[22:23], v11 offset0:12 offset1:14
	ds_read2_b32 v[28:29], v11 offset0:16 offset1:18
	ds_read2_b32 v[30:31], v11 offset0:20 offset1:22
	ds_read2_b32 v[32:33], v11 offset0:24 offset1:26
	ds_read2_b32 v[34:35], v11 offset0:28 offset1:30
	ds_read2_b32 v[60:61], v102 offset1:2
	ds_read2_b32 v[62:63], v104 offset1:2
	ds_read2_b32 v[64:65], v106 offset1:2
	ds_read2_b32 v[66:67], v102 offset0:4 offset1:6
	ds_read2_b32 v[68:69], v104 offset0:4 offset1:6
	ds_read2_b32 v[70:71], v106 offset0:4 offset1:6
	ds_read2_b32 v[72:73], v102 offset0:8 offset1:10
	ds_read2_b32 v[74:75], v104 offset0:8 offset1:10
	ds_read2_b32 v[76:77], v106 offset0:8 offset1:10
	ds_read2_b32 v[78:79], v102 offset0:12 offset1:14
	ds_read2_b32 v[80:81], v104 offset0:12 offset1:14
	ds_read2_b32 v[82:83], v106 offset0:12 offset1:14
	ds_read2_b32 v[84:85], v102 offset0:16 offset1:18
	ds_read2_b32 v[86:87], v104 offset0:16 offset1:18
	ds_read2_b32 v[88:89], v106 offset0:16 offset1:18
	ds_read2_b32 v[90:91], v102 offset0:20 offset1:22
	ds_read2_b32 v[92:93], v104 offset0:20 offset1:22
	ds_read2_b32 v[94:95], v106 offset0:20 offset1:22
	ds_read2_b32 v[96:97], v102 offset0:24 offset1:26
	ds_read2_b32 v[98:99], v104 offset0:24 offset1:26
	ds_read2_b32 v[100:101], v106 offset0:24 offset1:26
	ds_read2_b32 v[102:103], v102 offset0:28 offset1:30
	ds_read2_b32 v[104:105], v104 offset0:28 offset1:30
	ds_read2_b32 v[106:107], v106 offset0:28 offset1:30
	global_load_dword v108, v[108:109], off nt
	s_nop 0
	global_load_dword v110, v[110:111], off nt
	s_nop 0
	global_load_dword v112, v[112:113], off nt
	s_nop 0
	global_load_dword v114, v[114:115], off nt
	s_nop 0
	global_load_dword v116, v[116:117], off nt
	s_nop 0
	global_load_dword v118, v[118:119], off nt
	s_nop 0
	global_load_dword v120, v[120:121], off nt
	s_nop 0
	global_load_dword v122, v[122:123], off nt
	s_nop 0
	global_load_dword v124, v[124:125], off nt
	s_nop 0
	global_load_dword v126, v[126:127], off nt
	s_nop 0
	global_load_dword v128, v[128:129], off nt
	s_nop 0
	global_load_dword v130, v[130:131], off nt
	s_nop 0
	global_load_dword v132, v[132:133], off nt
	s_nop 0
	global_load_dword v134, v[134:135], off nt
	s_nop 0
	global_load_dword v136, v[136:137], off nt
	s_nop 0
	global_load_dword v138, v[138:139], off nt
	s_waitcnt lgkmcnt(14)
	v_mov_b32_e32 v140, v26
	v_mov_b32_e32 v141, v60
	v_mov_b32_e32 v142, v62
	v_mov_b32_e32 v143, v64
	v_mov_b32_e32 v60, v27
	v_mov_b32_e32 v64, v63
	v_mov_b32_e32 v26, v24
	v_mov_b32_e32 v27, v66
	v_mov_b32_e32 v62, v68
	v_mov_b32_e32 v63, v70
	v_mov_b32_e32 v66, v25
	v_mov_b32_e32 v70, v69
	v_mov_b32_e32 v24, v20
	v_mov_b32_e32 v25, v72
	v_mov_b32_e32 v68, v74
	v_mov_b32_e32 v69, v76
	v_mov_b32_e32 v72, v21
	v_mov_b32_e32 v76, v75
	v_mov_b32_e32 v20, v22
	v_mov_b32_e32 v21, v78
	s_waitcnt lgkmcnt(13)
	v_mov_b32_e32 v74, v80
	s_waitcnt lgkmcnt(12)
	v_mov_b32_e32 v75, v82
	v_mov_b32_e32 v78, v23
	v_mov_b32_e32 v82, v81
	v_mov_b32_e32 v22, v28
	s_waitcnt lgkmcnt(11)
	v_mov_b32_e32 v23, v84
	s_waitcnt lgkmcnt(10)
	v_mov_b32_e32 v80, v86
	s_waitcnt lgkmcnt(9)
	v_mov_b32_e32 v81, v88
	v_mov_b32_e32 v84, v29
	v_mov_b32_e32 v88, v87
	v_mov_b32_e32 v28, v30
	s_waitcnt lgkmcnt(8)
	v_mov_b32_e32 v29, v90
	s_waitcnt lgkmcnt(7)
	v_mov_b32_e32 v86, v92
	s_waitcnt lgkmcnt(6)
	v_mov_b32_e32 v87, v94
	v_mov_b32_e32 v90, v31
	v_mov_b32_e32 v94, v93
	v_mov_b32_e32 v30, v32
	s_waitcnt lgkmcnt(5)
	v_mov_b32_e32 v31, v96
	s_waitcnt lgkmcnt(4)
	v_mov_b32_e32 v92, v98
	s_waitcnt lgkmcnt(3)
	v_mov_b32_e32 v93, v100
	v_mov_b32_e32 v96, v33
	v_mov_b32_e32 v100, v99
	v_mov_b32_e32 v32, v34
	s_waitcnt lgkmcnt(2)
	v_mov_b32_e32 v33, v102
	v_mov_b32_e32 v102, v35
	s_waitcnt lgkmcnt(1)
	v_mov_b32_e32 v34, v104
	s_waitcnt lgkmcnt(0)
	v_mov_b32_e32 v35, v106
	s_add_i32 s9, s9, 32
	v_mov_b32_e32 v106, v105
	v_add_u32_e32 v11, 0x80, v11
	s_cmpk_gt_u32 s9, 0x7d
	s_waitcnt vmcnt(15)
	v_pk_fma_f32 v[16:17], v[108:109], v[140:141], v[16:17] op_sel_hi:[0,1,1]
	v_pk_fma_f32 v[18:19], v[108:109], v[142:143], v[18:19] op_sel_hi:[0,1,1]
	s_waitcnt vmcnt(14)
	v_pk_fma_f32 v[16:17], v[110:111], v[60:61], v[16:17] op_sel_hi:[0,1,1]
	v_pk_fma_f32 v[18:19], v[110:111], v[64:65], v[18:19] op_sel_hi:[0,1,1]
	s_waitcnt vmcnt(13)
	v_pk_fma_f32 v[16:17], v[112:113], v[26:27], v[16:17] op_sel_hi:[0,1,1]
	v_pk_fma_f32 v[18:19], v[112:113], v[62:63], v[18:19] op_sel_hi:[0,1,1]
	s_waitcnt vmcnt(12)
	v_pk_fma_f32 v[16:17], v[114:115], v[66:67], v[16:17] op_sel_hi:[0,1,1]
	v_pk_fma_f32 v[18:19], v[114:115], v[70:71], v[18:19] op_sel_hi:[0,1,1]
	s_waitcnt vmcnt(11)
	v_pk_fma_f32 v[16:17], v[116:117], v[24:25], v[16:17] op_sel_hi:[0,1,1]
	v_pk_fma_f32 v[18:19], v[116:117], v[68:69], v[18:19] op_sel_hi:[0,1,1]
	s_waitcnt vmcnt(10)
	v_pk_fma_f32 v[16:17], v[118:119], v[72:73], v[16:17] op_sel_hi:[0,1,1]
	v_pk_fma_f32 v[18:19], v[118:119], v[76:77], v[18:19] op_sel_hi:[0,1,1]
	s_waitcnt vmcnt(9)
	v_pk_fma_f32 v[16:17], v[120:121], v[20:21], v[16:17] op_sel_hi:[0,1,1]
	v_pk_fma_f32 v[18:19], v[120:121], v[74:75], v[18:19] op_sel_hi:[0,1,1]
	s_waitcnt vmcnt(8)
	v_pk_fma_f32 v[16:17], v[122:123], v[78:79], v[16:17] op_sel_hi:[0,1,1]
	v_pk_fma_f32 v[18:19], v[122:123], v[82:83], v[18:19] op_sel_hi:[0,1,1]
	s_waitcnt vmcnt(7)
	v_pk_fma_f32 v[16:17], v[124:125], v[22:23], v[16:17] op_sel_hi:[0,1,1]
	v_pk_fma_f32 v[18:19], v[124:125], v[80:81], v[18:19] op_sel_hi:[0,1,1]
	s_waitcnt vmcnt(6)
	v_pk_fma_f32 v[16:17], v[126:127], v[84:85], v[16:17] op_sel_hi:[0,1,1]
	v_pk_fma_f32 v[18:19], v[126:127], v[88:89], v[18:19] op_sel_hi:[0,1,1]
	s_waitcnt vmcnt(5)
	v_pk_fma_f32 v[16:17], v[128:129], v[28:29], v[16:17] op_sel_hi:[0,1,1]
	v_pk_fma_f32 v[18:19], v[128:129], v[86:87], v[18:19] op_sel_hi:[0,1,1]
	s_waitcnt vmcnt(4)
	v_pk_fma_f32 v[16:17], v[130:131], v[90:91], v[16:17] op_sel_hi:[0,1,1]
	v_pk_fma_f32 v[18:19], v[130:131], v[94:95], v[18:19] op_sel_hi:[0,1,1]
	s_waitcnt vmcnt(3)
	v_pk_fma_f32 v[16:17], v[132:133], v[30:31], v[16:17] op_sel_hi:[0,1,1]
	v_pk_fma_f32 v[18:19], v[132:133], v[92:93], v[18:19] op_sel_hi:[0,1,1]
	s_waitcnt vmcnt(2)
	v_pk_fma_f32 v[16:17], v[134:135], v[96:97], v[16:17] op_sel_hi:[0,1,1]
	v_pk_fma_f32 v[18:19], v[134:135], v[100:101], v[18:19] op_sel_hi:[0,1,1]
	s_waitcnt vmcnt(1)
	v_pk_fma_f32 v[16:17], v[136:137], v[32:33], v[16:17] op_sel_hi:[0,1,1]
	v_pk_fma_f32 v[18:19], v[136:137], v[34:35], v[18:19] op_sel_hi:[0,1,1]
	s_waitcnt vmcnt(0)
	v_pk_fma_f32 v[16:17], v[138:139], v[102:103], v[16:17] op_sel_hi:[0,1,1]
	v_pk_fma_f32 v[18:19], v[138:139], v[106:107], v[18:19] op_sel_hi:[0,1,1]
	s_cbranch_scc0 .LBB0_111
	v_and_b32_e32 v14, 64, v57
	v_xor_b32_e32 v11, 32, v57
	v_add_u32_e32 v14, 64, v14
	v_cmp_lt_i32_e32 vcc, v11, v14
	s_barrier
	s_nop 0
	v_cndmask_b32_e32 v11, v57, v11, vcc
	v_lshlrev_b32_e32 v20, 2, v11
	ds_bpermute_b32 v11, v20, v16
	ds_bpermute_b32 v14, v20, v17
	ds_bpermute_b32 v15, v20, v18
	ds_bpermute_b32 v20, v20, v19
	s_waitcnt lgkmcnt(0)
	s_and_saveexec_b64 s[26:27], s[6:7]
	s_cbranch_execz .LBB0_114
	v_add_f32_e32 v11, v16, v11
	v_add_f32_e32 v14, v17, v14
	v_add_f32_e32 v15, v18, v15
	v_add_f32_e32 v16, v19, v20
	ds_write2_b32 v36, v11, v14 offset1:32
	ds_write2_b32 v36, v15, v16 offset0:64 offset1:96
